# k36: k30 + layer-1 meta units moved to prompt-chain workgroups 0..7, layer-0 retention-chain workgroups run sample units 960..1023 and the 8 meta units before their chain
# speedup vs baseline: 1.0337x; 1.0052x over previous
; template <int TYPE>
; __device__ __forceinline__ void mix_sg_unit(Frame& F, int b, int h, int mode  , const float* rot) {
;     const bool prompt = (mode != 1);
;     const int tid = F.tid, lane = F.lane, w = F.wave, r16 = lane & 15, q = lane >> 4;
;     const int tk = tid >> 3, p = tid & 7;
;     LAS unsigned char* L = F.lds;
;     LAS float* OB = (LAS float*)(L + MX_OB); LAS float* RP = (LAS float*)(L + MX_RP); LAS float* DI = (LAS float*)(L + MX_DI);
;     bf16* MIX = F_XN(F);
;     const int qcol = (TYPE == 0 ? 0 : 2048) + 128 * h, kcol = (TYPE == 0 ? 512 : 2560) + 128 * h, vcol = (TYPE == 0 ? 1024 : 3072) + 128 * h, gcol = (TYPE == 0 ? 1536 : 3584) + 128 * h, mcol = (TYPE == 0 ? 0 : 512) + 128 * h;
;     f32x4 S[8]; f32x4 nacc = {0.f, 0.f, 0.f, 0.f}; float m0 = 0.f;
; #pragma unroll
;     for (int mt = 0; mt < 8; ++mt) S[mt] = (f32x4){0.f, 0.f, 0.f, 0.f};
;     if (!prompt) {
;         const float* Sin = (TYPE == 0 ? F.in[2] : F.in[5]) + (size_t)(b * 4 + h) * 16384;
; #pragma unroll
;         for (int mt = 0; mt < 8; ++mt)
; #pragma unroll
;             for (int r = 0; r < 4; ++r) S[mt][r] = __builtin_nontemporal_load(Sin + (16 * mt + 4 * q + r) * 128 + 16 * w + r16);
;         if (TYPE == 0) {
; #pragma unroll
;             for (int r = 0; r < 4; ++r) nacc[r] = F.in[3][(size_t)(b * 4 + h) * 128 + 16 * w + 4 * q + r];
;             m0 = F.in[4][b * 4 + h];
;         }
;     }
;     const float lgam = (TYPE != 1) ? 0.f : h == 0 ? -0.031748698314580298f : h == 1 ? -0.015748356968139168f : h == 2 ? -0.0078431774610258928f : -0.0039138993211363287f;
;     const float bias_i = (TYPE == 0) ? F.in[11][h] : 0.f, bias_f = (TYPE == 0) ? F.in[12][h] : 0.f;
;     LAS float* GN = (LAS float*)(L + MX_GN);
;     if (tid < 128) GN[tid] = (TYPE == 0 ? F.in[13] : F.in[14])[128 * h + tid];
;     const int nsc = (mode == 0) ? 33 : 1;
; __device__ __forceinline__ void mixer_layer0(Frame& F) {
;     ...
;     int bid = blockIdx.x; asm volatile("" : "+s"(bid));
;     if (bid < 64) { const int u = bid, ty = u >> 5, bh = u & 31; if (ty == 0) mix_sg_unit<0>(F, bh >> 2, bh & 3, 0, rot); else mix_sg_unit<1>(F, bh >> 2, bh & 3, 0, rot); return; }
; #pragma unroll 1
;     for (int u = bid - 64; u < 1024 + 8; u += F.G - 64) {
;         int ty, bh, mode;
;         if (u < 1024) { ty = u >> 9; bh = u & 511; mode = 1; } else { ty = (u - 1024) >> 2; bh = (u - 1024) & 3; mode = 2; }
.LBB0_713:
	s_cmp_gt_i32 s81, 1
	s_mov_b32 s81, 0x800000
	s_cbranch_scc0 .LBB0_899
	v_mov_b32_e32 v145, v206
	v_readlane_b32 s0, v255, 7
	v_readlane_b32 s1, v255, 8
	v_readfirstlane_b32 s47, v145
	v_and_b32_e32 v190, 63, v145
	s_ashr_i32 s46, s47, 6
	s_andn2_b64 vcc, exec, s[0:1]
	s_mov_b64 s[0:1], -1
	s_cbranch_vccnz .LBB0_847
	s_mov_b32 s78, s42
	s_cmp_gt_i32 s78, 31
	s_cbranch_scc0 .LBB0_767
	s_mov_b32 s79, s48
	s_mov_b32 s48, s39
	s_cmpk_gt_u32 s78, 0x447
	s_cbranch_scc1 .LBB0_766
	s_lshl_b32 s40, s46, 4
	s_ashr_i32 s41, s40, 31
	v_readlane_b32 s56, v251, 5
	s_sub_i32 s43, s78, 64
	s_mov_b32 s100, s87
	s_movk_i32 s101, 0x3ff
	s_cmp_gt_i32 s78, 63
	s_cbranch_scc1 .Lmx0_side
	s_add_i32 s43, s78, 0x3a0
	s_movk_i32 s100, 32
	s_movk_i32 s101, 0x407
.Lmx0_side:
	s_lshl_b64 s[0:1], s[40:41], 2
	v_readlane_b32 s66, v251, 15
	s_waitcnt vmcnt(0) lgkmcnt(0)
	v_and_b32_e32 v4, 15, v145
	v_readlane_b32 s67, v251, 16
	s_add_u32 s4, s66, s0
	v_and_b32_e32 v5, 7, v145
	s_addc_u32 s5, s67, s1
	v_lshlrev_b32_e32 v2, 2, v4
	v_lshlrev_b32_e32 v6, 2, v145
	v_readlane_b32 s6, v253, 62
	v_lshl_add_u64 v[0:1], s[4:5], 0, v[2:3]
	s_movk_i32 s4, 0x80
	v_add_u32_e32 v87, s6, v6
	v_lshlrev_b32_e32 v64, 4, v5
	v_and_b32_e32 v6, 4, v6
	s_movk_i32 s5, 0x60
	v_ashrrev_i32_e32 v65, 3, v145
	v_cmp_gt_i32_e64 s[38:39], s4, v145
	s_movk_i32 s4, 0x110
	v_and_or_b32 v6, v64, s5, v6
	s_movk_i32 s5, 0x210
	v_lshrrev_b32_e32 v8, 4, v190
	v_mul_lo_u32 v7, v65, s4
	v_lshlrev_b32_e32 v66, 5, v5
	v_lshlrev_b32_e32 v92, 1, v6
	v_mul_lo_u32 v6, v65, s5
	v_lshlrev_b32_e32 v5, 6, v5
	v_readlane_b32 s5, v253, 63
	v_add_u32_e32 v91, 0, v7
	v_bfe_u32 v7, v145, 2, 2
	v_add3_u32 v93, s5, v6, v5
	v_lshlrev_b32_e32 v6, 2, v8
	v_or_b32_e32 v7, v6, v7
	v_mad_u32_u24 v96, v7, s4, 0
	v_lshlrev_b32_e32 v7, 3, v145
	v_readlane_b32 s68, v251, 17
	v_readlane_b32 s69, v251, 18
	v_and_b32_e32 v98, 24, v7
	v_or_b32_e32 v7, 2, v6
	v_readlane_b32 s64, v251, 13
	v_readlane_b32 s65, v251, 14
	v_readlane_b32 s70, v251, 19
	v_readlane_b32 s71, v251, 20
	v_cmp_gt_u32_e64 s[68:69], v7, v4
	v_or_b32_e32 v7, 3, v6
	v_mad_u32_u24 v94, v4, s4, 0
	v_cmp_gt_u32_e64 s[64:65], v6, v4
	v_cmp_lt_u32_e64 s[66:67], v6, v4
	v_cmp_gt_u32_e64 s[70:71], v7, v4
	v_cmp_eq_u32_e64 s[72:73], 0, v4
	v_and_b32_e32 v4, -16, v190
	v_readlane_b32 s4, v254, 1
	s_cmp_lt_u32 s47, 64
	s_cselect_b64 s[50:51], -1, 0
	v_add_u32_e32 v107, s4, v4
	v_readlane_b32 s4, v254, 2
	s_lshl_b32 s14, s46, 6
	s_add_i32 s14, s14, s5
	v_add_u32_e32 v108, s4, v4
	v_readlane_b32 s4, v254, 3
	v_readlane_b32 s60, v251, 9
	v_readlane_b32 s61, v251, 10
	v_add_u32_e32 v109, s4, v4
	v_readlane_b32 s4, v252, 61
	s_add_u32 s41, s4, s0
	v_readlane_b32 s4, v252, 62
	s_addc_u32 s44, s4, s1
	v_and_b32_e32 v9, 12, v2
	s_add_u32 s26, s60, s0
	v_readlane_b32 s62, v251, 11
	v_or_b32_e32 v7, s40, v9
	v_add_u32_e32 v103, s6, v5
	v_readlane_b32 s6, v254, 0
	s_addc_u32 s27, s61, s1
	v_readlane_b32 s63, v251, 12
	v_lshlrev_b32_e32 v99, 1, v7
	v_add_u32_e32 v105, s6, v6
	v_lshl_add_u64 v[6:7], s[26:27], 0, v[2:3]
	s_add_u32 s26, s62, s0
	s_addc_u32 s27, s63, s1
	s_lshl_b32 s29, s46, 2
	v_mov_b32_e32 v5, v3
	v_readlane_b32 s5, v254, 5
	s_and_b32 s29, s29, 4
	v_add_u32_e32 v101, s14, v2
	v_add_u32_e32 v106, s6, v2
	v_lshl_add_u64 v[68:69], s[26:27], 0, v[4:5]
	v_lshlrev_b32_e32 v5, 2, v65
	v_readlane_b32 s4, v254, 4
	v_add_u32_e32 v112, s5, v2
	s_and_b32 s28, s40, 0xffffffe0
	v_lshl_or_b32 v2, v8, 3, s29
	s_lshl_b32 s34, s46, 8
	v_add_u32_e32 v110, s4, v5
	v_add_u32_e32 v111, s5, v5
	v_or_b32_e32 v10, s46, v8
	v_or_b32_e32 v2, s28, v2
	s_add_i32 s34, s4, s34
	v_readlane_b32 s4, v252, 57
	v_cmp_eq_u32_e64 s[26:27], 0, v10
	v_lshlrev_b32_e32 v10, 1, v2
	v_lshl_or_b32 v2, v9, 1, s29
	v_mov_b32_e32 v67, v3
	v_readlane_b32 s5, v252, 58
	v_or_b32_e32 v2, s28, v2
	v_add_u32_e32 v113, s34, v4
	v_lshl_add_u64 v[70:71], s[4:5], 0, v[66:67]
	v_readlane_b32 s4, v253, 1
	v_lshlrev_b32_e32 v4, 1, v2
	s_add_u32 s45, s4, s0
	v_readlane_b32 s0, v253, 2
	v_cmp_eq_u32_e32 vcc, 0, v190
	v_lshlrev_b32_e32 v2, 11, v8
	v_lshlrev_b32_e32 v90, 13, v65
	v_and_b32_e32 v95, 48, v145
	v_lshl_add_u32 v97, s46, 5, v96
	v_lshlrev_b32_e32 v100, 2, v9
	v_mul_u32_u24_e32 v102, 0x840, v8
	v_cmp_eq_u32_e64 s[84:85], 2, v8
	v_cmp_eq_u32_e64 s[96:97], 1, v8
	v_cmp_gt_u32_e64 s[20:21], 16, v190
	v_lshl_add_u32 v104, v190, 2, s6
	v_cmp_gt_i32_e64 s[22:23], 16, v65
	v_cmp_lt_i32_e64 s[24:25], 15, v65
	v_readlane_b32 s62, v254, 6
	v_add_u32_e32 v67, s6, v5
	s_addc_u32 s49, s0, s1
	s_and_b64 s[54:55], s[50:51], vcc
	v_lshl_add_u64 v[72:73], v[0:1], 0, v[2:3]
	v_lshl_add_u64 v[74:75], v[6:7], 0, v[2:3]
	v_add_u32_e32 v114, v94, v10
	v_add_u32_e32 v115, v96, v4
	v_readlane_b32 s57, v251, 6
	v_readlane_b32 s58, v251, 7
	v_readlane_b32 s59, v251, 8
	s_branch .LBB0_720

; __device__ __forceinline__ void mixer_layer0(Frame& F) {
;     ...
;     for (int u = bid - 64; u < 1024 + 8; u += F.G - 64) {
;         int ty, bh, mode;
;         if (u < 1024) { ty = u >> 9; bh = u & 511; mode = 1; } else { ty = (u - 1024) >> 2; bh = (u - 1024) & 3; mode = 2; }
;         if (ty == 0) mix_sg_unit<0>(F, bh >> 2, bh & 3, mode, rot); else mix_sg_unit<1>(F, bh >> 2, bh & 3, mode, rot);
;     }
.LBB0_719:
	s_add_i32 s43, s43, s100
	s_cmp_gt_i32 s43, s101
	s_cbranch_scc1 .LBB0_766
.LBB0_720:
	s_cmp_lt_i32 s78, 64
	s_cbranch_scc1 .Lmx0_go
	s_cmpk_lt_i32 s43, 0x3c0
	s_cbranch_scc1 .Lmx0_go
	s_cmpk_gt_i32 s43, 0x3ff
	s_cbranch_scc0 .LBB0_719

; __device__ __forceinline__ void mixer_layer0(Frame& F) {
;     ...
;     if (bid < 64) { const int u = bid, ty = u >> 5, bh = u & 31; if (ty == 0) mix_sg_unit<0>(F, bh >> 2, bh & 3, 0, rot); else mix_sg_unit<1>(F, bh >> 2, bh & 3, 0, rot); return; }
; #pragma unroll 1
;     for (int u = bid - 64; u < 1024 + 8; u += F.G - 64) {
;         int ty, bh, mode;
;         if (u < 1024) { ty = u >> 9; bh = u & 511; mode = 1; } else { ty = (u - 1024) >> 2; bh = (u - 1024) & 3; mode = 2; }
;         if (ty == 0) mix_sg_unit<0>(F, bh >> 2, bh & 3, mode, rot); else mix_sg_unit<1>(F, bh >> 2, bh & 3, mode, rot);
;     }
.LBB0_766:
	v_readlane_b32 s66, v254, 30
	v_readlane_b32 s72, v254, 32
	v_readlane_b32 s96, v254, 34
	v_readlane_b32 s64, v252, 3
	v_readlane_b32 s62, v253, 29
	v_readlane_b32 s68, v253, 37
	s_cmp_lt_i32 s78, 64
	s_cselect_b64 s[0:1], -1, 0
	v_readlane_b32 s67, v254, 31
	s_mov_b32 s39, s48
	v_readlane_b32 s73, v254, 33
	v_readlane_b32 s97, v254, 35
	s_mov_b32 s48, s79
	v_readlane_b32 s65, v252, 4
	v_readlane_b32 s63, v253, 30
	v_readlane_b32 s69, v253, 38
	v_readlane_b32 s70, v253, 39
	v_readlane_b32 s71, v253, 40

; #define LAS __attribute__((address_space(3)))
; __device__ __forceinline__ void mix_hg_unit(Frame& F, int b, int h, int mode) {
;     ...
;     const int tid = F.tid, lane = F.lane, w = F.wave, r16 = lane & 15, q = lane >> 4;
;     const int tk = tid >> 3, p = tid & 7;
;     LAS unsigned char* L = F.lds;
;     LAS float* GD = (LAS float*)(L + MX_GD); LAS float* OB = (LAS float*)(L + MX_OB);
;     bf16* MIX = F_XN(F);
;     f32x4 S[8];
; #pragma unroll
;     for (int mt = 0; mt < 8; ++mt) S[mt] = (f32x4){0.f, 0.f, 0.f, 0.f};
;     if (!prompt) {
;         const float* Sin = F.in[6] + (size_t)(b * 8 + h) * 16384;
; #pragma unroll
;         for (int mt = 0; mt < 8; ++mt)
; #pragma unroll
;             for (int r = 0; r < 4; ++r) S[mt][r] = __builtin_nontemporal_load(Sin + (16 * mt + 4 * q + r) * 128 + 16 * w + r16);
;     }
;     LAS float* GN = (LAS float*)(L + MX_GN);
;     if (tid < 128) GN[tid] = F.in[18][128 * h + tid];
;     const int nsc = (mode == 0) ? 33 : 1;
;     u32x4 pa[6]; u32x4 pg[2]; float pgd = 1.f;
;     ...
;     const int zvo = tk * 8192 + (128 * h + 16 * p) * 2;
; __device__ __forceinline__ void mixer_layer1(Frame& F) {
;     ...
;     if (bid < 64) { mix_hg_unit(F, bid >> 3, bid & 7, 0); return; }
; #pragma unroll 1
;     for (int u = bid - 64; u < 1024 + 8; u += F.G - 64) {
;         if (u < 1024) mix_hg_unit(F, u >> 3, u & 7, 1); else mix_hg_unit(F, 0, u - 1024, 2);
.LBB0_847:
	s_andn2_b64 vcc, exec, s[0:1]
	s_cbranch_vccnz .LBB0_898
	s_mov_b32 s0, s42
	s_mov_b64 s[4:5], -1
	s_cmpk_gt_u32 s0, 0x447
	s_cbranch_scc1 .LBB0_874
	s_waitcnt vmcnt(0) lgkmcnt(0)
	v_ashrrev_i32_e32 v4, 7, v145
	v_ashrrev_i32_e32 v5, 31, v4
	v_readlane_b32 s10, v253, 19
	s_movk_i32 s1, 0x80
	v_cmp_gt_i32_e64 s[8:9], 1, v4
	v_lshlrev_b64 v[4:5], 12, v[4:5]
	v_and_b32_e32 v6, 0x7f, v145
	v_readlane_b32 s11, v253, 20
	v_and_b32_e32 v1, 7, v145
	v_cmp_gt_i32_e64 s[4:5], s1, v145
	s_movk_i32 s1, 0x7f
	v_lshlrev_b32_e32 v9, 2, v145
	v_lshl_add_u64 v[4:5], s[10:11], 0, v[4:5]
	v_lshlrev_b32_e32 v2, 2, v6
	v_cmp_lt_i32_e64 s[6:7], s1, v145
	v_lshlrev_b32_e32 v106, 4, v1
	v_lshl_add_u64 v[4:5], v[4:5], 0, v[2:3]
	v_and_b32_e32 v2, 4, v9
	s_movk_i32 s1, 0x60
	v_ashrrev_i32_e32 v0, 3, v145
	v_and_or_b32 v2, v106, s1, v2
	s_movk_i32 s12, 0x110
	v_lshlrev_b32_e32 v107, 1, v2
	v_mul_lo_u32 v2, v0, s12
	s_movk_i32 s15, 0x210
	v_lshrrev_b32_e32 v8, 4, v190
	v_readlane_b32 s13, v253, 62
	v_add_u32_e32 v108, 0, v2
	v_lshlrev_b32_e32 v94, 5, v1
	v_mul_lo_u32 v2, v0, s15
	v_lshlrev_b32_e32 v1, 6, v1
	v_readlane_b32 s14, v253, 63
	s_mov_b64 s[10:11], 0x440000
	v_readlane_b32 s25, v254, 7
	v_add3_u32 v110, s14, v2, v1
	v_add_u32_e32 v111, s13, v1
	v_lshlrev_b32_e32 v1, 2, v8
	v_add_u32_e32 v104, s13, v9
	v_lshl_add_u64 v[92:93], v[4:5], 0, s[10:11]
	v_add_u32_e32 v109, s25, v9
	v_or_b32_e32 v4, 3, v1
	v_mov_b32_e32 v9, 0xfffffdf0
	v_and_b32_e32 v7, 15, v145
	v_readlane_b32 s10, v252, 57
	s_and_b32 s1, s47, 0xffffffc0
	v_mad_u32_u24 v115, v4, s15, v9
	v_bfe_u32 v9, v145, 2, 2
	v_mov_b32_e32 v95, v3
	v_readlane_b32 s11, v252, 58
	s_add_i32 s1, s1, s14
	v_or_b32_e32 v5, 2, v1
	v_or_b32_e32 v9, v1, v9
	v_cmp_lt_u32_e64 s[14:15], v1, v7
	v_cmp_gt_u32_e64 s[16:17], v1, v7
	v_ashrrev_i32_e32 v1, 31, v0
	v_lshl_add_u64 v[96:97], s[10:11], 0, v[94:95]
	v_mad_u32_u24 v95, v7, s12, 0
	v_mul_u32_u24_e32 v114, 0x210, v4
	v_mad_u32_u24 v9, v9, s12, 0
	v_cmp_gt_u32_e64 s[10:11], v4, v7
	v_cmp_gt_u32_e64 s[12:13], v5, v7
	v_lshlrev_b64 v[4:5], 11, v[0:1]
	v_lshl_add_u64 v[4:5], v[96:97], 0, v[4:5]
	s_mov_b64 s[22:23], 0x2200000
	v_lshl_add_u64 v[98:99], v[4:5], 0, s[22:23]
	s_lshl_b32 s22, s46, 4
	s_ashr_i32 s23, s22, 31
	s_mov_b32 s43, s71
	v_readlane_b32 s56, v251, 5
	s_sub_i32 s24, s0, 64
	s_mov_b32 s100, s87
	s_movk_i32 s101, 0x3ff
	s_cmp_gt_i32 s0, 63
	s_cbranch_scc1 .Lmx1_side
	s_add_i32 s24, s0, 0x3c0
	s_movk_i32 s100, 64
	s_movk_i32 s101, 0x407

; __device__ __forceinline__ void mixer_layer1(Frame& F) {
;     ...
; #pragma unroll 1
;     for (int u = bid - 64; u < 1024 + 8; u += F.G - 64) {
;         if (u < 1024) mix_hg_unit(F, u >> 3, u & 7, 1); else mix_hg_unit(F, 0, u - 1024, 2);
.Lmx1_side2:
	v_add_u32_e32 v121, 0xfffbc000, v0
	s_cmp_gt_i32 s0, 63
	s_cbranch_scc1 .Lmx1_side3
	v_add_u32_e32 v121, 0xffffc000, v0
.Lmx1_side3:
	v_lshlrev_b32_e32 v122, 2, v6
	v_add_u32_e32 v123, v9, v1
	v_add_u32_e32 v124, v9, v7
	v_add_u32_e32 v125, v9, v10
	v_readlane_b32 s57, v251, 6
	v_readlane_b32 s58, v251, 7
	v_readlane_b32 s59, v251, 8
	v_readlane_b32 s60, v251, 9
	v_readlane_b32 s61, v251, 10
	v_readlane_b32 s70, v251, 19
	v_readlane_b32 s67, v254, 31
	s_branch .LBB0_853

; __device__ __forceinline__ void mixer_layer1(Frame& F) {
;     ...
; #pragma unroll 1
;     for (int u = bid - 64; u < 1024 + 8; u += F.G - 64) {
;         if (u < 1024) mix_hg_unit(F, u >> 3, u & 7, 1); else mix_hg_unit(F, 0, u - 1024, 2);
.LBB0_852:
	v_readlane_b32 s25, v253, 50
	s_cmp_lt_i32 s0, 64
	s_cselect_b32 s25, 0x2000, s25
	s_add_i32 s26, s26, s25
	s_add_i32 s24, s24, s100
	v_readlane_b32 s25, v253, 51
	s_cmp_lt_i32 s0, 64
	s_cselect_b32 s25, 0x4000, s25
	s_cmp_gt_i32 s24, s101
	s_nop 0
	v_add_u32_e32 v121, s25, v121
	s_cbranch_scc1 .LBB0_874
